# attention: K/V rings split (3 K slots, 4 V slots), LDS-DMA prefetch 2 tiles ahead with counted vmcnt(6), DMA issue moved after the last QK MFMA
# speedup vs baseline: 1.0033x; 1.0033x over previous
; #define ATT_ISSUE(tilebase, bufbase) do { const unsigned char* _tb = (tilebase); asm volatile("" : "+s"(_tb)); _Pragma("unroll") for (int _i = 0; _i < 6; ++_i) { int _q = wave + 8 * _i; _q = _q > 44 ? 44 : _q; \
;         __builtin_amdgcn_global_load_lds((const unsigned*)(_tb + goff[_i]), (LAS unsigned*)((bufbase) + _q * 1024), 16, 0, 0); } } while (0)
; __device__ __forceinline__ void att_mfma(const Params& P, LAS unsigned char* lds, int wave) {
;     ...
;     for (int u = blockIdx.x; u < 1024; u += gridDim.x) {
;         const int bh = u & 63, r = u >> 6, kk = r >> 2, j4 = r & 3;
;         const int qb = kk == 0 ? j4 : (kk == 1 ? 15 - j4 : (kk == 2 ? 4 + j4 : 11 - j4));
;         const int b = bh >> 3, hh = bh & 7;
;         const int ntile = 4 * qb + 4, my_last = 4 * qb + w4;
;         const size_t qrow_g = (size_t)b * SEQ + qb * 256 + w4 * 64 + (wave >> 2) * 32 + q32;
;         const unsigned char* kvb = (const unsigned char*)(KV + (size_t)b * SEQ * 2560 + hh * 320);
;         ATT_ISSUE(kvb, lds);
;         bf16x8 qf[12];
;         { const bf16_t* qp = Q + qrow_g * 1536 + hh * 192 + hf * 8;
; #pragma unroll
;           for (int ks = 0; ks < 12; ++ks) qf[ks] = *(const bf16x8*)(qp + ks * 16); }
;     ...
;         {
;             float qv[12][8]; float sq = 0.f;
; #pragma unroll
;             for (int ks = 0; ks < 12; ++ks)
; #pragma unroll
;                 for (int e = 0; e < 8; ++e) { qv[ks][e] = bf2f((unsigned short)qf[ks][e]); sq += qv[ks][e] * qv[ks][e]; }
;             { const auto rr = __builtin_amdgcn_permlane32_swap(__float_as_uint(sq), __float_as_uint(sq), false, false);
;               sq = __uint_as_float(rr[0]) + __uint_as_float(rr[1]); }
;             const float rs = __builtin_amdgcn_rsqf(sq * (1.f / 192.f) + EPS) * (0.07216878364870322f * 1.4426950408889634f);
.LBB0_1014:
	s_bfe_u32 s5, s73, 0x3000c
	s_and_b32 s6, s38, 7
	s_mul_i32 s5, s5, 0x1400000
	s_mulk_i32 s6, 0x280
	s_or_b32 s5, s5, s6
	s_add_u32 s10, s25, s5
	s_addc_u32 s11, s26, 0
	s_lshl_b32 s5, s39, 9
	s_lshl_b32 s51, s4, 2
	s_and_b32 s6, s5, 0x7000
	s_and_b32 s47, s39, 7
	s_add_i32 s50, s51, 4
	s_lshl_b32 s16, s4, 8
	s_mul_i32 s4, s6, 0x1400
	s_add_u32 s4, s48, s4
	s_addc_u32 s5, s49, 0
	s_mul_i32 s17, s47, 0x280
	s_add_u32 s4, s4, s17
	s_addc_u32 s5, s5, 0
	s_add_i32 s16, s16, s6
	v_add_u32_e32 v164, s16, v224
	s_mul_i32 s6, s47, 0x180
	s_mov_b32 s17, 2
	s_mov_b32 s61, 1
	s_mov_b32 s16, 0
	s_mov_b32 s74, 0
	s_movk_i32 s75, 0x6400
	s_mov_b32 s76, 0xc800
	s_mov_b32 s78, 0xc800
	s_mov_b32 s79, 0x11800
	s_mov_b32 s80, 0x16800
	s_mov_b32 s77, 0x1b800
	s_add_u32 s10, s10, 0x50000
	s_addc_u32 s11, s11, 0
	s_cmp_eq_u32 s33, 0
	s_cselect_b32 s82, s74, s78
	s_add_i32 m0, s74, s19
	v_lshl_add_u64 v[0:1], s[4:5], 0, v[144:145]
	global_load_lds_dwordx4 v[0:1], off
	s_add_i32 m0, s74, s20
	v_lshl_add_u64 v[0:1], s[4:5], 0, v[146:147]
	global_load_lds_dwordx4 v[0:1], off
	s_add_i32 m0, s74, s21
	v_lshl_add_u64 v[0:1], s[4:5], 0, v[148:149]
	global_load_lds_dwordx4 v[0:1], off
	s_add_i32 m0, s82, s22
	v_lshl_add_u64 v[0:1], s[4:5], 0, v[150:151]
	global_load_lds_dwordx4 v[0:1], off
	s_add_i32 m0, s78, s23
	v_lshl_add_u64 v[0:1], s[4:5], 0, v[156:157]
	global_load_lds_dwordx4 v[0:1], off
	s_add_i32 m0, s78, s24
	v_lshl_add_u64 v[0:1], s[4:5], 0, v[154:155]
	global_load_lds_dwordx4 v[0:1], off
	s_add_u32 s4, s4, 0x50000
	s_addc_u32 s5, s5, 0
	s_cmp_eq_u32 s33, 0
	s_cselect_b32 s82, s75, s79
	s_add_i32 m0, s75, s19
	v_lshl_add_u64 v[0:1], s[4:5], 0, v[144:145]
	global_load_lds_dwordx4 v[0:1], off
	s_add_i32 m0, s75, s20
	v_lshl_add_u64 v[0:1], s[4:5], 0, v[146:147]
	global_load_lds_dwordx4 v[0:1], off
	s_add_i32 m0, s75, s21
	v_lshl_add_u64 v[0:1], s[4:5], 0, v[148:149]
	global_load_lds_dwordx4 v[0:1], off
	s_add_i32 m0, s82, s22
	v_lshl_add_u64 v[0:1], s[4:5], 0, v[150:151]
	global_load_lds_dwordx4 v[0:1], off
	s_add_i32 m0, s79, s23
	v_lshl_add_u64 v[0:1], s[4:5], 0, v[156:157]
	global_load_lds_dwordx4 v[0:1], off
	s_add_i32 m0, s79, s24
	v_lshl_add_u64 v[0:1], s[4:5], 0, v[154:155]
	global_load_lds_dwordx4 v[0:1], off
	v_mad_u64_u32 v[0:1], s[4:5], v164, s35, v[166:167]
	v_lshl_add_u64 v[0:1], v[0:1], 0, s[6:7]
	v_lshl_add_u64 v[0:1], v[158:159], 1, v[0:1]
	flat_load_dwordx4 v[104:107], v[0:1]
	flat_load_dwordx4 v[108:111], v[0:1] offset:32
	flat_load_dwordx4 v[112:115], v[0:1] offset:64
	flat_load_dwordx4 v[116:119], v[0:1] offset:96
	flat_load_dwordx4 v[208:211], v[0:1] offset:128
	flat_load_dwordx4 v[200:203], v[0:1] offset:160
	flat_load_dwordx4 v[192:195], v[0:1] offset:192
	flat_load_dwordx4 v[184:187], v[0:1] offset:224
	flat_load_dwordx4 v[174:177], v[0:1] offset:256
	flat_load_dwordx4 v[132:135], v[0:1] offset:288
	flat_load_dwordx4 v[178:181], v[0:1] offset:320
	flat_load_dwordx4 v[138:141], v[0:1] offset:352
	s_waitcnt vmcnt(0) lgkmcnt(0)
	s_barrier
	v_lshlrev_b32_e32 v0, 7, v164
	v_mov_b32_e32 v1, v165
	v_and_b32_e32 v0, 0x7ff80, v0
	v_lshl_add_u64 v[142:143], v[162:163], 0, v[0:1]
	v_add_co_u32_e32 v246, vcc, s36, v142
	s_or_b32 s6, s51, s18
	s_nop 0
	v_addc_co_u32_e32 v247, vcc, 0, v143, vcc
	s_add_i32 s51, s6, 1
	s_mov_b32 s58, 0
	s_waitcnt vmcnt(0) lgkmcnt(0)
	s_nop 0
	v_and_b32_e32 v235, 0xffff0000, v104
	v_lshlrev_b32_e32 v234, 16, v104
	v_mul_f32_e32 v104, v235, v235
	v_and_b32_e32 v243, 0xffff0000, v105
	v_lshlrev_b32_e32 v242, 16, v105
	v_pk_fma_f32 v[104:105], v[234:235], v[234:235], v[104:105] op_sel_hi:[1,1,0]
	v_and_b32_e32 v233, 0xffff0000, v106
	v_lshlrev_b32_e32 v232, 16, v106
	v_pk_fma_f32 v[104:105], v[242:243], v[242:243], v[104:105]
	v_mul_f32_e32 v106, v243, v243
	v_pk_add_f32 v[104:105], v[106:107], v[104:105] op_sel_hi:[0,1]
	v_pk_fma_f32 v[104:105], v[232:233], v[232:233], v[104:105]
	v_mul_f32_e32 v106, v233, v233
	v_and_b32_e32 v241, 0xffff0000, v107
	v_lshlrev_b32_e32 v240, 16, v107
	v_pk_add_f32 v[104:105], v[106:107], v[104:105] op_sel_hi:[0,1]
	v_pk_fma_f32 v[104:105], v[240:241], v[240:241], v[104:105]
	v_mul_f32_e32 v106, v241, v241
	v_and_b32_e32 v219, 0xffff0000, v111
	v_lshlrev_b32_e32 v218, 16, v111
	v_and_b32_e32 v221, 0xffff0000, v110
	v_lshlrev_b32_e32 v220, 16, v110
	v_and_b32_e32 v111, 0xffff0000, v109
	v_lshlrev_b32_e32 v110, 16, v109
	v_and_b32_e32 v109, 0xffff0000, v108
	v_lshlrev_b32_e32 v108, 16, v108
	v_pk_add_f32 v[104:105], v[106:107], v[104:105] op_sel_hi:[0,1]
	v_pk_fma_f32 v[104:105], v[108:109], v[108:109], v[104:105]
	v_mul_f32_e32 v106, v109, v109
	v_pk_add_f32 v[104:105], v[106:107], v[104:105] op_sel_hi:[0,1]
	v_pk_fma_f32 v[104:105], v[110:111], v[110:111], v[104:105]
	v_mul_f32_e32 v106, v111, v111
	v_pk_add_f32 v[104:105], v[106:107], v[104:105] op_sel_hi:[0,1]
	v_pk_fma_f32 v[104:105], v[220:221], v[220:221], v[104:105]
	v_mul_f32_e32 v106, v221, v221
	v_pk_add_f32 v[104:105], v[106:107], v[104:105] op_sel_hi:[0,1]
	v_pk_fma_f32 v[104:105], v[218:219], v[218:219], v[104:105]
	v_mul_f32_e32 v106, v219, v219
	v_and_b32_e32 v215, 0xffff0000, v115
	v_lshlrev_b32_e32 v214, 16, v115
	v_and_b32_e32 v217, 0xffff0000, v114
	v_lshlrev_b32_e32 v216, 16, v114
	v_and_b32_e32 v115, 0xffff0000, v113
	v_lshlrev_b32_e32 v114, 16, v113
	v_and_b32_e32 v113, 0xffff0000, v112
	v_lshlrev_b32_e32 v112, 16, v112
	v_pk_add_f32 v[104:105], v[106:107], v[104:105] op_sel_hi:[0,1]
	v_pk_fma_f32 v[104:105], v[112:113], v[112:113], v[104:105]
	v_mul_f32_e32 v106, v113, v113
	v_pk_add_f32 v[104:105], v[106:107], v[104:105] op_sel_hi:[0,1]
	v_pk_fma_f32 v[104:105], v[114:115], v[114:115], v[104:105]
; __device__ __forceinline__ void att_mfma(const Params& P, LAS unsigned char* lds, int wave) {
;     ...
;             float qv[12][8]; float sq = 0.f;
; #pragma unroll
;             for (int ks = 0; ks < 12; ++ks)
; #pragma unroll
;                 for (int e = 0; e < 8; ++e) { qv[ks][e] = bf2f((unsigned short)qf[ks][e]); sq += qv[ks][e] * qv[ks][e]; }
;             { const auto rr = __builtin_amdgcn_permlane32_swap(__float_as_uint(sq), __float_as_uint(sq), false, false);
;               sq = __uint_as_float(rr[0]) + __uint_as_float(rr[1]); }
;             const float rs = __builtin_amdgcn_rsqf(sq * (1.f / 192.f) + EPS) * (0.07216878364870322f * 1.4426950408889634f);
;             const float* qg = (const float*)(ws + WS_SMALL) + 2048 + 8 * hf;
;             const int spos = (int)(qrow_g & (SEQ - 1));
;             const float* cM = (const float*)(ws + WS_ROPE_M) + spos * 32 + 8 * hf; const float* sM = cM + 4096 * 32;
; #pragma unroll
;             for (int ks = 0; ks < 12; ++ks) { const f32x4 g0 = *(const f32x4*)(qg + 16 * ks), g1 = *(const f32x4*)(qg + 16 * ks + 4);
	v_mul_f32_e32 v106, v115, v115
	v_pk_add_f32 v[104:105], v[106:107], v[104:105] op_sel_hi:[0,1]
	v_pk_fma_f32 v[104:105], v[216:217], v[216:217], v[104:105]
	v_mul_f32_e32 v106, v217, v217
	v_pk_add_f32 v[104:105], v[106:107], v[104:105] op_sel_hi:[0,1]
	v_pk_fma_f32 v[104:105], v[214:215], v[214:215], v[104:105]
	v_mul_f32_e32 v106, v215, v215
	v_and_b32_e32 v131, 0xffff0000, v133
	v_lshlrev_b32_e32 v130, 16, v133
	v_and_b32_e32 v127, 0xffff0000, v139
	v_lshlrev_b32_e32 v126, 16, v139
	v_and_b32_e32 v137, 0xffff0000, v132
	v_lshlrev_b32_e32 v136, 16, v132
	v_and_b32_e32 v133, 0xffff0000, v138
	v_lshlrev_b32_e32 v132, 16, v138
	v_and_b32_e32 v139, 0xffff0000, v177
	v_lshlrev_b32_e32 v138, 16, v177
	v_and_b32_e32 v171, 0xffff0000, v176
	v_lshlrev_b32_e32 v170, 16, v176
	v_and_b32_e32 v173, 0xffff0000, v175
	v_lshlrev_b32_e32 v172, 16, v175
	v_and_b32_e32 v169, 0xffff0000, v179
	v_lshlrev_b32_e32 v168, 16, v179
	v_and_b32_e32 v177, 0xffff0000, v174
	v_lshlrev_b32_e32 v176, 16, v174
	v_and_b32_e32 v175, 0xffff0000, v178
	v_lshlrev_b32_e32 v174, 16, v178
	v_and_b32_e32 v179, 0xffff0000, v187
	v_lshlrev_b32_e32 v178, 16, v187
	v_and_b32_e32 v183, 0xffff0000, v186
	v_lshlrev_b32_e32 v182, 16, v186
	v_and_b32_e32 v187, 0xffff0000, v195
	v_lshlrev_b32_e32 v186, 16, v195
	v_and_b32_e32 v191, 0xffff0000, v194
	v_lshlrev_b32_e32 v190, 16, v194
	v_and_b32_e32 v195, 0xffff0000, v203
	v_lshlrev_b32_e32 v194, 16, v203
	v_and_b32_e32 v199, 0xffff0000, v202
	v_lshlrev_b32_e32 v198, 16, v202
	v_and_b32_e32 v203, 0xffff0000, v211
	v_lshlrev_b32_e32 v202, 16, v211
	v_and_b32_e32 v207, 0xffff0000, v210
	v_lshlrev_b32_e32 v206, 16, v210
	v_and_b32_e32 v211, 0xffff0000, v119
	v_lshlrev_b32_e32 v210, 16, v119
	v_and_b32_e32 v213, 0xffff0000, v118
	v_lshlrev_b32_e32 v212, 16, v118
	v_and_b32_e32 v119, 0xffff0000, v117
	v_lshlrev_b32_e32 v118, 16, v117
	v_and_b32_e32 v117, 0xffff0000, v116
	v_lshlrev_b32_e32 v116, 16, v116
	v_pk_add_f32 v[104:105], v[106:107], v[104:105] op_sel_hi:[0,1]
	v_pk_fma_f32 v[104:105], v[116:117], v[116:117], v[104:105]
	v_mul_f32_e32 v106, v117, v117
	v_pk_add_f32 v[104:105], v[106:107], v[104:105] op_sel_hi:[0,1]
	v_pk_fma_f32 v[104:105], v[118:119], v[118:119], v[104:105]
	v_mul_f32_e32 v106, v119, v119
	v_pk_add_f32 v[104:105], v[106:107], v[104:105] op_sel_hi:[0,1]
	v_pk_fma_f32 v[104:105], v[212:213], v[212:213], v[104:105]
	v_mul_f32_e32 v106, v213, v213
	v_pk_add_f32 v[104:105], v[106:107], v[104:105] op_sel_hi:[0,1]
	v_pk_fma_f32 v[104:105], v[210:211], v[210:211], v[104:105]
	v_mul_f32_e32 v106, v211, v211
	v_and_b32_e32 v205, 0xffff0000, v209
	v_lshlrev_b32_e32 v204, 16, v209
	v_and_b32_e32 v209, 0xffff0000, v208
	v_lshlrev_b32_e32 v208, 16, v208
	v_pk_add_f32 v[104:105], v[106:107], v[104:105] op_sel_hi:[0,1]
	v_pk_fma_f32 v[104:105], v[208:209], v[208:209], v[104:105]
	v_mul_f32_e32 v106, v209, v209
	v_pk_add_f32 v[104:105], v[106:107], v[104:105] op_sel_hi:[0,1]
	v_pk_fma_f32 v[104:105], v[204:205], v[204:205], v[104:105]
	v_mul_f32_e32 v106, v205, v205
	v_pk_add_f32 v[104:105], v[106:107], v[104:105] op_sel_hi:[0,1]
	v_pk_fma_f32 v[104:105], v[206:207], v[206:207], v[104:105]
	v_mul_f32_e32 v106, v207, v207
	v_pk_add_f32 v[104:105], v[106:107], v[104:105] op_sel_hi:[0,1]
	v_pk_fma_f32 v[104:105], v[202:203], v[202:203], v[104:105]
	v_mul_f32_e32 v106, v203, v203
	v_and_b32_e32 v197, 0xffff0000, v201
	v_lshlrev_b32_e32 v196, 16, v201
	v_and_b32_e32 v201, 0xffff0000, v200
	v_lshlrev_b32_e32 v200, 16, v200
	v_pk_add_f32 v[104:105], v[106:107], v[104:105] op_sel_hi:[0,1]
	v_pk_fma_f32 v[104:105], v[200:201], v[200:201], v[104:105]
	v_mul_f32_e32 v106, v201, v201
	v_pk_add_f32 v[104:105], v[106:107], v[104:105] op_sel_hi:[0,1]
	v_pk_fma_f32 v[104:105], v[196:197], v[196:197], v[104:105]
	v_mul_f32_e32 v106, v197, v197
	v_pk_add_f32 v[104:105], v[106:107], v[104:105] op_sel_hi:[0,1]
	v_pk_fma_f32 v[104:105], v[198:199], v[198:199], v[104:105]
	v_mul_f32_e32 v106, v199, v199
	v_pk_add_f32 v[104:105], v[106:107], v[104:105] op_sel_hi:[0,1]
	v_pk_fma_f32 v[104:105], v[194:195], v[194:195], v[104:105]
	v_mul_f32_e32 v106, v195, v195
	v_and_b32_e32 v189, 0xffff0000, v193
	v_lshlrev_b32_e32 v188, 16, v193
	v_and_b32_e32 v193, 0xffff0000, v192
	v_lshlrev_b32_e32 v192, 16, v192
	v_pk_add_f32 v[104:105], v[106:107], v[104:105] op_sel_hi:[0,1]
	v_pk_fma_f32 v[104:105], v[192:193], v[192:193], v[104:105]
	v_mul_f32_e32 v106, v193, v193
	flat_load_dwordx4 v[100:103], v[160:161]
	flat_load_dwordx4 v[96:99], v[160:161] offset:16
	flat_load_dwordx4 v[92:95], v[160:161] offset:64
	flat_load_dwordx4 v[88:91], v[160:161] offset:80
	flat_load_dwordx4 v[84:87], v[160:161] offset:128
	flat_load_dwordx4 v[80:83], v[160:161] offset:144
	flat_load_dwordx4 v[76:79], v[160:161] offset:192
	flat_load_dwordx4 v[72:75], v[160:161] offset:208
	flat_load_dwordx4 v[68:71], v[160:161] offset:256
	flat_load_dwordx4 v[64:67], v[160:161] offset:272
	flat_load_dwordx4 v[60:63], v[160:161] offset:320
	flat_load_dwordx4 v[56:59], v[160:161] offset:336
	flat_load_dwordx4 v[52:55], v[160:161] offset:384
	flat_load_dwordx4 v[48:51], v[160:161] offset:400
	flat_load_dwordx4 v[44:47], v[160:161] offset:448
	flat_load_dwordx4 v[40:43], v[160:161] offset:464
	flat_load_dwordx4 v[36:39], v[160:161] offset:512
	flat_load_dwordx4 v[32:35], v[160:161] offset:528
	flat_load_dwordx4 v[28:31], v[160:161] offset:576
	flat_load_dwordx4 v[24:27], v[160:161] offset:592
	flat_load_dwordx4 v[20:23], v[160:161] offset:640
	flat_load_dwordx4 v[16:19], v[160:161] offset:656
	flat_load_dwordx4 v[12:15], v[160:161] offset:704
	flat_load_dwordx4 v[8:11], v[160:161] offset:720
; __device__ __forceinline__ void att_mfma(const Params& P, LAS unsigned char* lds, int wave) {
;     ...
;                 for (int e = 0; e < 8; ++e) { qv[ks][e] = bf2f((unsigned short)qf[ks][e]); sq += qv[ks][e] * qv[ks][e]; }
;             { const auto rr = __builtin_amdgcn_permlane32_swap(__float_as_uint(sq), __float_as_uint(sq), false, false);
;               sq = __uint_as_float(rr[0]) + __uint_as_float(rr[1]); }
;             const float rs = __builtin_amdgcn_rsqf(sq * (1.f / 192.f) + EPS) * (0.07216878364870322f * 1.4426950408889634f);
;             const float* qg = (const float*)(ws + WS_SMALL) + 2048 + 8 * hf;
;             const int spos = (int)(qrow_g & (SEQ - 1));
;             const float* cM = (const float*)(ws + WS_ROPE_M) + spos * 32 + 8 * hf; const float* sM = cM + 4096 * 32;
; #pragma unroll
;             for (int ks = 0; ks < 12; ++ks) { const f32x4 g0 = *(const f32x4*)(qg + 16 * ks), g1 = *(const f32x4*)(qg + 16 * ks + 4);
; #pragma unroll
;                 for (int e = 0; e < 4; ++e) { qv[ks][e] *= rs * g0[e]; qv[ks][4 + e] *= rs * g1[e]; } }
	flat_load_dwordx4 v[4:7], v[142:143]
	flat_load_dwordx4 v[0:3], v[142:143] offset:16
	v_pk_add_f32 v[104:105], v[106:107], v[104:105] op_sel_hi:[0,1]
	v_pk_fma_f32 v[104:105], v[188:189], v[188:189], v[104:105]
	v_mul_f32_e32 v106, v189, v189
	v_pk_add_f32 v[104:105], v[106:107], v[104:105] op_sel_hi:[0,1]
	v_pk_fma_f32 v[104:105], v[190:191], v[190:191], v[104:105]
	v_mul_f32_e32 v106, v191, v191
	v_pk_add_f32 v[104:105], v[106:107], v[104:105] op_sel_hi:[0,1]
	v_pk_fma_f32 v[104:105], v[186:187], v[186:187], v[104:105]
	v_mul_f32_e32 v106, v187, v187
	v_and_b32_e32 v123, 0xffff0000, v135
	v_lshlrev_b32_e32 v122, 16, v135
	v_and_b32_e32 v121, 0xffff0000, v141
	v_lshlrev_b32_e32 v120, 16, v141
	v_and_b32_e32 v129, 0xffff0000, v134
	v_lshlrev_b32_e32 v128, 16, v134
	v_and_b32_e32 v125, 0xffff0000, v140
	v_lshlrev_b32_e32 v124, 16, v140
	v_and_b32_e32 v135, 0xffff0000, v181
	v_lshlrev_b32_e32 v134, 16, v181
	v_and_b32_e32 v141, 0xffff0000, v180
	v_lshlrev_b32_e32 v140, 16, v180
	v_and_b32_e32 v181, 0xffff0000, v185
	v_lshlrev_b32_e32 v180, 16, v185
	v_and_b32_e32 v185, 0xffff0000, v184
	v_lshlrev_b32_e32 v184, 16, v184
	v_pk_add_f32 v[104:105], v[106:107], v[104:105] op_sel_hi:[0,1]
	v_pk_fma_f32 v[104:105], v[184:185], v[184:185], v[104:105]
	v_mul_f32_e32 v106, v185, v185
	v_pk_add_f32 v[104:105], v[106:107], v[104:105] op_sel_hi:[0,1]
	v_pk_fma_f32 v[104:105], v[180:181], v[180:181], v[104:105]
	v_mul_f32_e32 v106, v181, v181
	v_pk_add_f32 v[104:105], v[106:107], v[104:105] op_sel_hi:[0,1]
	v_pk_fma_f32 v[104:105], v[182:183], v[182:183], v[104:105]
	v_mul_f32_e32 v106, v183, v183
	v_pk_add_f32 v[104:105], v[106:107], v[104:105] op_sel_hi:[0,1]
	v_pk_fma_f32 v[104:105], v[178:179], v[178:179], v[104:105]
	v_mul_f32_e32 v106, v179, v179
	v_pk_add_f32 v[104:105], v[106:107], v[104:105] op_sel_hi:[0,1]
	v_pk_fma_f32 v[104:105], v[176:177], v[176:177], v[104:105]
	v_mul_f32_e32 v106, v177, v177
	v_pk_add_f32 v[104:105], v[106:107], v[104:105] op_sel_hi:[0,1]
	v_pk_fma_f32 v[104:105], v[172:173], v[172:173], v[104:105]
	v_mul_f32_e32 v106, v173, v173
	v_pk_add_f32 v[104:105], v[106:107], v[104:105] op_sel_hi:[0,1]
	v_pk_fma_f32 v[104:105], v[170:171], v[170:171], v[104:105]
	v_mul_f32_e32 v106, v171, v171
	v_pk_add_f32 v[104:105], v[106:107], v[104:105] op_sel_hi:[0,1]
	v_pk_fma_f32 v[104:105], v[138:139], v[138:139], v[104:105]
	v_mul_f32_e32 v106, v139, v139
	v_pk_add_f32 v[104:105], v[106:107], v[104:105] op_sel_hi:[0,1]
	v_pk_fma_f32 v[104:105], v[136:137], v[136:137], v[104:105]
	v_mul_f32_e32 v106, v137, v137
	v_pk_add_f32 v[104:105], v[106:107], v[104:105] op_sel_hi:[0,1]
	v_pk_fma_f32 v[104:105], v[130:131], v[130:131], v[104:105]
	v_mul_f32_e32 v106, v131, v131
	v_pk_add_f32 v[104:105], v[106:107], v[104:105] op_sel_hi:[0,1]
	v_pk_fma_f32 v[104:105], v[128:129], v[128:129], v[104:105]
	v_mul_f32_e32 v106, v129, v129
	v_pk_add_f32 v[104:105], v[106:107], v[104:105] op_sel_hi:[0,1]
	v_pk_fma_f32 v[104:105], v[122:123], v[122:123], v[104:105]
	v_mul_f32_e32 v106, v123, v123
	v_pk_add_f32 v[104:105], v[106:107], v[104:105] op_sel_hi:[0,1]
	v_pk_fma_f32 v[104:105], v[174:175], v[174:175], v[104:105]
	v_mul_f32_e32 v106, v175, v175
	v_pk_add_f32 v[104:105], v[106:107], v[104:105] op_sel_hi:[0,1]
	v_pk_fma_f32 v[104:105], v[168:169], v[168:169], v[104:105]
	v_mul_f32_e32 v106, v169, v169
	v_pk_add_f32 v[104:105], v[106:107], v[104:105] op_sel_hi:[0,1]
	v_pk_fma_f32 v[104:105], v[140:141], v[140:141], v[104:105]
	v_mul_f32_e32 v106, v141, v141
	v_pk_add_f32 v[104:105], v[106:107], v[104:105] op_sel_hi:[0,1]
	v_pk_fma_f32 v[104:105], v[134:135], v[134:135], v[104:105]
	v_mul_f32_e32 v106, v135, v135
	v_pk_add_f32 v[104:105], v[106:107], v[104:105] op_sel_hi:[0,1]
	v_pk_fma_f32 v[104:105], v[132:133], v[132:133], v[104:105]
	v_mul_f32_e32 v106, v133, v133
	v_pk_add_f32 v[104:105], v[106:107], v[104:105] op_sel_hi:[0,1]
	v_pk_fma_f32 v[104:105], v[126:127], v[126:127], v[104:105]
	v_mul_f32_e32 v106, v127, v127
	v_pk_add_f32 v[104:105], v[106:107], v[104:105] op_sel_hi:[0,1]
	v_pk_fma_f32 v[104:105], v[124:125], v[124:125], v[104:105]
	v_mul_f32_e32 v106, v125, v125
	v_pk_add_f32 v[104:105], v[106:107], v[104:105] op_sel_hi:[0,1]
	v_pk_fma_f32 v[104:105], v[120:121], v[120:121], v[104:105]
	v_mul_f32_e32 v106, v121, v121
	v_pk_add_f32 v[104:105], v[106:107], v[104:105] op_sel_hi:[0,1]
	v_mov_b32_e32 v105, v104
	s_nop 1
	v_permlane32_swap_b32_e32 v104, v105
	v_add_f32_e32 v104, v104, v105
	v_fmamk_f32 v104, v104, 0x3baaaaab, v225
	v_rsq_f32_e32 v227, v104
	flat_load_dwordx4 v[104:107], v[246:247]
	flat_load_dwordx4 v[228:231], v[246:247] offset:16
	v_mul_f32_e32 v248, 0x3dd53b94, v227
	s_waitcnt vmcnt(0) lgkmcnt(0)
; __device__ __forceinline__ void att_mfma(const Params& P, LAS unsigned char* lds, int wave) {
;     ...
; #pragma unroll
;             for (int ks = 0; ks < 12; ++ks) { const f32x4 g0 = *(const f32x4*)(qg + 16 * ks), g1 = *(const f32x4*)(qg + 16 * ks + 4);
; #pragma unroll
;                 for (int e = 0; e < 4; ++e) { qv[ks][e] *= rs * g0[e]; qv[ks][4 + e] *= rs * g1[e]; } }
; #pragma unroll
;             for (int k2 = 0; k2 < 2; ++k2) {
;                 const f32x4 c0 = *(const f32x4*)(cM + 16 * k2), c1 = *(const f32x4*)(cM + 16 * k2 + 4), s0 = *(const f32x4*)(sM + 16 * k2), s1 = *(const f32x4*)(sM + 16 * k2 + 4);
; #pragma unroll
;                 for (int e = 0; e < 8; ++e) { const float cc = e < 4 ? c0[e & 3] : c1[e & 3], ss = e < 4 ? s0[e & 3] : s1[e & 3];
;                     const float a = qv[8 + k2][e], bq = qv[10 + k2][e]; qv[8 + k2][e] = a * cc - bq * ss; qv[10 + k2][e] = bq * cc + a * ss; }
;             }
	v_pk_mul_f32 v[96:97], v[96:97], v[248:249] op_sel_hi:[1,0]
	v_pk_mul_f32 v[100:101], v[100:101], v[248:249] op_sel_hi:[1,0]
	v_pk_mul_f32 v[252:253], v[96:97], v[232:233]
	v_pk_mul_f32 v[96:97], v[102:103], v[248:249] op_sel_hi:[1,0]
	v_pk_mul_f32 v[250:251], v[100:101], v[234:235]
	flat_load_dwordx4 v[232:235], v[142:143] offset:64
	flat_load_dwordx4 v[236:239], v[142:143] offset:80
	v_pk_mul_f32 v[142:143], v[96:97], v[242:243]
	v_pk_mul_f32 v[242:243], v[98:99], v[248:249] op_sel_hi:[1,0]
	flat_load_dwordx4 v[96:99], v[246:247] offset:64
	flat_load_dwordx4 v[100:103], v[246:247] offset:80
	v_pk_mul_f32 v[20:21], v[248:249], v[20:21] op_sel_hi:[0,1]
	v_pk_mul_f32 v[92:93], v[92:93], v[248:249] op_sel_hi:[1,0]
	v_pk_mul_f32 v[36:37], v[248:249], v[36:37] op_sel_hi:[0,1]
	v_pk_mul_f32 v[20:21], v[20:21], v[174:175]
	v_pk_mul_f32 v[92:93], v[92:93], v[108:109]
	v_pk_mul_f32 v[36:37], v[36:37], v[176:177]
	v_pk_mul_f32 v[38:39], v[248:249], v[38:39] op_sel_hi:[0,1]
	v_pk_mul_f32 v[24:25], v[248:249], v[24:25] op_sel_hi:[0,1]
	v_pk_mul_f32 v[22:23], v[248:249], v[22:23] op_sel_hi:[0,1]
	v_pk_mul_f32 v[38:39], v[38:39], v[172:173]
	v_pk_mul_f32 v[24:25], v[24:25], v[128:129]
	v_pk_mul_f32 v[16:17], v[248:249], v[16:17] op_sel_hi:[0,1]
	v_pk_mul_f32 v[22:23], v[22:23], v[168:169]
	v_pk_mul_f32 v[32:33], v[248:249], v[32:33] op_sel_hi:[0,1]
	v_pk_mul_f32 v[16:17], v[16:17], v[140:141]
	v_pk_mul_f32 v[32:33], v[32:33], v[170:171]
	v_pk_mul_f32 v[34:35], v[248:249], v[34:35] op_sel_hi:[0,1]
	v_pk_mul_f32 v[18:19], v[248:249], v[18:19] op_sel_hi:[0,1]
	v_pk_mul_f32 v[34:35], v[34:35], v[138:139]
	v_pk_mul_f32 v[18:19], v[18:19], v[134:135]
	v_pk_mul_f32 v[12:13], v[248:249], v[12:13] op_sel_hi:[0,1]
	v_pk_mul_f32 v[28:29], v[248:249], v[28:29] op_sel_hi:[0,1]
	v_pk_mul_f32 v[12:13], v[12:13], v[132:133]
	v_pk_mul_f32 v[28:29], v[28:29], v[136:137]
	v_pk_mul_f32 v[14:15], v[248:249], v[14:15] op_sel_hi:[0,1]
	v_pk_mul_f32 v[30:31], v[248:249], v[30:31] op_sel_hi:[0,1]
	v_pk_mul_f32 v[14:15], v[14:15], v[126:127]
	v_pk_mul_f32 v[30:31], v[30:31], v[130:131]
	v_pk_mul_f32 v[8:9], v[248:249], v[8:9] op_sel_hi:[0,1]
	v_pk_mul_f32 v[8:9], v[8:9], v[124:125]
	v_pk_mul_f32 v[10:11], v[248:249], v[10:11] op_sel_hi:[0,1]
	v_pk_mul_f32 v[26:27], v[248:249], v[26:27] op_sel_hi:[0,1]
	v_pk_mul_f32 v[10:11], v[10:11], v[120:121]
	v_pk_mul_f32 v[26:27], v[26:27], v[122:123]
	v_pk_mul_f32 v[60:61], v[248:249], v[60:61] op_sel_hi:[0,1]
	v_pk_mul_f32 v[56:57], v[248:249], v[56:57] op_sel_hi:[0,1]
	v_pk_mul_f32 v[62:63], v[248:249], v[62:63] op_sel_hi:[0,1]
	v_pk_mul_f32 v[58:59], v[248:249], v[58:59] op_sel_hi:[0,1]
	v_pk_mul_f32 v[52:53], v[248:249], v[52:53] op_sel_hi:[0,1]
	v_pk_mul_f32 v[48:49], v[248:249], v[48:49] op_sel_hi:[0,1]
	v_pk_mul_f32 v[54:55], v[248:249], v[54:55] op_sel_hi:[0,1]
	v_pk_mul_f32 v[50:51], v[248:249], v[50:51] op_sel_hi:[0,1]
	v_pk_mul_f32 v[44:45], v[248:249], v[44:45] op_sel_hi:[0,1]
	v_pk_mul_f32 v[40:41], v[248:249], v[40:41] op_sel_hi:[0,1]
	v_pk_mul_f32 v[46:47], v[248:249], v[46:47] op_sel_hi:[0,1]
	v_pk_mul_f32 v[42:43], v[248:249], v[42:43] op_sel_hi:[0,1]
	v_pk_mul_f32 v[88:89], v[88:89], v[248:249] op_sel_hi:[1,0]
	v_pk_mul_f32 v[94:95], v[94:95], v[248:249] op_sel_hi:[1,0]
	v_pk_mul_f32 v[90:91], v[90:91], v[248:249] op_sel_hi:[1,0]
	v_pk_mul_f32 v[84:85], v[84:85], v[248:249] op_sel_hi:[1,0]
	v_pk_mul_f32 v[80:81], v[248:249], v[80:81] op_sel_hi:[0,1]
	v_pk_mul_f32 v[86:87], v[86:87], v[248:249] op_sel_hi:[1,0]
	v_pk_mul_f32 v[82:83], v[248:249], v[82:83] op_sel_hi:[0,1]
	v_pk_mul_f32 v[76:77], v[248:249], v[76:77] op_sel_hi:[0,1]
	v_pk_mul_f32 v[72:73], v[248:249], v[72:73] op_sel_hi:[0,1]
	v_pk_mul_f32 v[78:79], v[248:249], v[78:79] op_sel_hi:[0,1]
	v_pk_mul_f32 v[74:75], v[248:249], v[74:75] op_sel_hi:[0,1]
	v_pk_mul_f32 v[68:69], v[248:249], v[68:69] op_sel_hi:[0,1]
	v_pk_mul_f32 v[64:65], v[248:249], v[64:65] op_sel_hi:[0,1]
	v_pk_mul_f32 v[70:71], v[248:249], v[70:71] op_sel_hi:[0,1]
	v_pk_mul_f32 v[66:67], v[248:249], v[66:67] op_sel_hi:[0,1]
	v_pk_mul_f32 v[60:61], v[60:61], v[200:201]
	v_pk_mul_f32 v[56:57], v[56:57], v[198:199]
	v_pk_mul_f32 v[62:63], v[62:63], v[196:197]
	v_pk_mul_f32 v[58:59], v[58:59], v[194:195]
	v_pk_mul_f32 v[52:53], v[52:53], v[192:193]
	v_pk_mul_f32 v[108:109], v[20:21], v[104:105]
	v_pk_mul_f32 v[48:49], v[48:49], v[190:191]
	v_pk_fma_f32 v[128:129], v[36:37], v[4:5], v[108:109] neg_lo:[0,0,1] neg_hi:[0,0,1]
	v_pk_mul_f32 v[36:37], v[36:37], v[104:105]
	v_pk_mul_f32 v[54:55], v[54:55], v[188:189]
	v_pk_fma_f32 v[4:5], v[20:21], v[4:5], v[36:37]
	v_pk_mul_f32 v[20:21], v[22:23], v[106:107]
	v_pk_mul_f32 v[36:37], v[38:39], v[106:107]
	v_pk_fma_f32 v[20:21], v[38:39], v[6:7], v[20:21] neg_lo:[0,0,1] neg_hi:[0,0,1]
	v_pk_fma_f32 v[6:7], v[22:23], v[6:7], v[36:37]
	v_pk_mul_f32 v[22:23], v[16:17], v[228:229]
	v_pk_mul_f32 v[50:51], v[50:51], v[186:187]
	v_pk_fma_f32 v[22:23], v[32:33], v[0:1], v[22:23] neg_lo:[0,0,1] neg_hi:[0,0,1]
	v_pk_mul_f32 v[32:33], v[32:33], v[228:229]
	v_pk_mul_f32 v[44:45], v[44:45], v[184:185]
	v_pk_fma_f32 v[0:1], v[16:17], v[0:1], v[32:33]
	v_pk_mul_f32 v[16:17], v[18:19], v[230:231]
	v_pk_mul_f32 v[32:33], v[34:35], v[230:231]
	v_pk_fma_f32 v[16:17], v[34:35], v[2:3], v[16:17] neg_lo:[0,0,1] neg_hi:[0,0,1]
	v_pk_fma_f32 v[2:3], v[18:19], v[2:3], v[32:33]
	s_waitcnt vmcnt(0) lgkmcnt(0)
; __device__ __forceinline__ void att_mfma(const Params& P, LAS unsigned char* lds, int wave) {
;     ...
;         f32x16 o[4];
; #pragma unroll
;         for (int d = 0; d < 4; ++d)
; #pragma unroll
;             for (int i = 0; i < 16; ++i) o[d][i] = 0.f;
;         float mrun = -1e30f, lrun = 0.f;
;         bf16x8 pb[4];
; #pragma unroll
;         for (int i = 0; i < 4; ++i) pb[i] = (bf16x8){0, 0, 0, 0, 0, 0, 0, 0};
;         ATT_BAR();
; #pragma unroll
;         for (int ks = 0; ks < 12; ++ks) asm volatile("" : "+v"(qf[ks]));
;         {
;             float qv[12][8]; float sq = 0.f;
; #pragma unroll
;             for (int ks = 0; ks < 12; ++ks)
; #pragma unroll
;                 for (int e = 0; e < 8; ++e) { qv[ks][e] = bf2f((unsigned short)qf[ks][e]); sq += qv[ks][e] * qv[ks][e]; }
;             { const auto rr = __builtin_amdgcn_permlane32_swap(__float_as_uint(sq), __float_as_uint(sq), false, false);
;               sq = __uint_as_float(rr[0]) + __uint_as_float(rr[1]); }
;             const float rs = __builtin_amdgcn_rsqf(sq * (1.f / 192.f) + EPS) * (0.07216878364870322f * 1.4426950408889634f);
;             const float* qg = (const float*)(ws + WS_SMALL) + 2048 + 8 * hf;
;             const int spos = (int)(qrow_g & (SEQ - 1));
;             const float* cM = (const float*)(ws + WS_ROPE_M) + spos * 32 + 8 * hf; const float* sM = cM + 4096 * 32;
; #pragma unroll
;             for (int ks = 0; ks < 12; ++ks) { const f32x4 g0 = *(const f32x4*)(qg + 16 * ks), g1 = *(const f32x4*)(qg + 16 * ks + 4);
; #pragma unroll
;                 for (int e = 0; e < 4; ++e) { qv[ks][e] *= rs * g0[e]; qv[ks][4 + e] *= rs * g1[e]; } }
; #pragma unroll
;             for (int k2 = 0; k2 < 2; ++k2) {
;                 const f32x4 c0 = *(const f32x4*)(cM + 16 * k2), c1 = *(const f32x4*)(cM + 16 * k2 + 4), s0 = *(const f32x4*)(sM + 16 * k2), s1 = *(const f32x4*)(sM + 16 * k2 + 4);
; #pragma unroll
;                 for (int e = 0; e < 8; ++e) { const float cc = e < 4 ? c0[e & 3] : c1[e & 3], ss = e < 4 ? s0[e & 3] : s1[e & 3];
;                     const float a = qv[8 + k2][e], bq = qv[10 + k2][e]; qv[8 + k2][e] = a * cc - bq * ss; qv[10 + k2][e] = bq * cc + a * ss; }
;             }
; #pragma unroll
;             for (int ks = 0; ks < 12; ++ks) qf[ks] = pack8bf(qv[ks][0], qv[ks][1], qv[ks][2], qv[ks][3], qv[ks][4], qv[ks][5], qv[ks][6], qv[ks][7]);
;         }
	v_pk_mul_f32 v[18:19], v[12:13], v[96:97]
	v_pk_mul_f32 v[40:41], v[40:41], v[182:183]
	v_pk_fma_f32 v[18:19], v[28:29], v[232:233], v[18:19] neg_lo:[0,0,1] neg_hi:[0,0,1]
	v_pk_mul_f32 v[28:29], v[28:29], v[96:97]
	v_pk_mul_f32 v[46:47], v[46:47], v[180:181]
	v_pk_fma_f32 v[12:13], v[12:13], v[232:233], v[28:29]
	v_pk_mul_f32 v[28:29], v[14:15], v[98:99]
	v_pk_mul_f32 v[42:43], v[42:43], v[178:179]
	v_pk_fma_f32 v[28:29], v[30:31], v[234:235], v[28:29] neg_lo:[0,0,1] neg_hi:[0,0,1]
	v_pk_mul_f32 v[30:31], v[30:31], v[98:99]
	v_pk_mul_f32 v[240:241], v[242:243], v[240:241]
	v_pk_fma_f32 v[14:15], v[14:15], v[234:235], v[30:31]
	v_pk_mul_f32 v[30:31], v[8:9], v[100:101]
	v_cvt_pk_bf16_f32 v141, v14, v15
	v_pk_fma_f32 v[30:31], v[24:25], v[236:237], v[30:31] neg_lo:[0,0,1] neg_hi:[0,0,1]
	v_pk_mul_f32 v[24:25], v[24:25], v[100:101]
	v_mov_b32_e32 v14, v165
	v_pk_fma_f32 v[8:9], v[8:9], v[236:237], v[24:25]
	v_pk_mul_f32 v[24:25], v[10:11], v[102:103]
	v_mov_b32_e32 v15, v165
	v_pk_fma_f32 v[24:25], v[26:27], v[238:239], v[24:25] neg_lo:[0,0,1] neg_hi:[0,0,1]
	v_pk_mul_f32 v[26:27], v[26:27], v[102:103]
	v_pk_mul_f32 v[88:89], v[88:89], v[220:221]
	v_pk_fma_f32 v[10:11], v[10:11], v[238:239], v[26:27]
	v_pk_mul_f32 v[94:95], v[94:95], v[110:111]
	v_pk_mul_f32 v[90:91], v[90:91], v[218:219]
	v_pk_mul_f32 v[84:85], v[84:85], v[112:113]
	v_pk_mul_f32 v[80:81], v[80:81], v[216:217]
	v_pk_mul_f32 v[86:87], v[86:87], v[114:115]
	v_pk_mul_f32 v[82:83], v[82:83], v[214:215]
	v_pk_mul_f32 v[76:77], v[76:77], v[116:117]
	v_pk_mul_f32 v[72:73], v[72:73], v[212:213]
	v_pk_mul_f32 v[78:79], v[78:79], v[118:119]
	v_pk_mul_f32 v[74:75], v[74:75], v[210:211]
	v_pk_mul_f32 v[68:69], v[68:69], v[208:209]
	v_pk_mul_f32 v[64:65], v[64:65], v[206:207]
	v_pk_mul_f32 v[70:71], v[70:71], v[204:205]
	v_pk_mul_f32 v[66:67], v[66:67], v[202:203]
	v_cvt_pk_bf16_f32 v97, v142, v143
	v_cvt_pk_bf16_f32 v116, v60, v61
	v_cvt_pk_bf16_f32 v117, v62, v63
	v_cvt_pk_bf16_f32 v118, v56, v57
	v_cvt_pk_bf16_f32 v119, v58, v59
	v_cvt_pk_bf16_f32 v120, v52, v53
	v_cvt_pk_bf16_f32 v121, v54, v55
	v_cvt_pk_bf16_f32 v122, v48, v49
	v_cvt_pk_bf16_f32 v123, v50, v51
	v_cvt_pk_bf16_f32 v124, v44, v45
	v_cvt_pk_bf16_f32 v125, v46, v47
	v_cvt_pk_bf16_f32 v126, v40, v41
	v_cvt_pk_bf16_f32 v127, v42, v43
	v_cvt_pk_bf16_f32 v128, v128, v129
	v_cvt_pk_bf16_f32 v129, v20, v21
	v_cvt_pk_bf16_f32 v130, v22, v23
	v_cvt_pk_bf16_f32 v131, v16, v17
	v_cvt_pk_bf16_f32 v132, v18, v19
	v_cvt_pk_bf16_f32 v133, v28, v29
	v_cvt_pk_bf16_f32 v134, v30, v31
	v_cvt_pk_bf16_f32 v135, v24, v25
	v_cvt_pk_bf16_f32 v136, v4, v5
	v_cvt_pk_bf16_f32 v137, v6, v7
	v_cvt_pk_bf16_f32 v138, v0, v1
	v_cvt_pk_bf16_f32 v139, v2, v3
	v_cvt_pk_bf16_f32 v140, v12, v13
	v_cvt_pk_bf16_f32 v142, v8, v9
	v_cvt_pk_bf16_f32 v143, v10, v11
	v_mov_b32_e32 v0, v165
	v_mov_b32_e32 v1, v165
	v_mov_b32_e32 v2, v165
	v_mov_b32_e32 v3, v165
	v_mov_b32_e32 v4, v165
	v_mov_b32_e32 v5, v165
	v_mov_b32_e32 v6, v165
	v_mov_b32_e32 v7, v165
	v_mov_b32_e32 v8, v165
	v_mov_b32_e32 v9, v165
	v_mov_b32_e32 v10, v165
	v_mov_b32_e32 v11, v165
	v_mov_b32_e32 v12, v165
	v_mov_b32_e32 v13, v165
	v_mov_b64_e32 v[30:31], v[14:15]
	v_mov_b64_e32 v[46:47], v[14:15]
	v_mov_b64_e32 v[62:63], v[14:15]
	v_cvt_pk_bf16_f32 v96, v250, v251
	v_cvt_pk_bf16_f32 v98, v252, v253
	v_cvt_pk_bf16_f32 v99, v240, v241
	v_cvt_pk_bf16_f32 v100, v92, v93
	v_cvt_pk_bf16_f32 v101, v94, v95
	v_cvt_pk_bf16_f32 v102, v88, v89
	v_cvt_pk_bf16_f32 v103, v90, v91
	v_cvt_pk_bf16_f32 v104, v84, v85
	v_cvt_pk_bf16_f32 v105, v86, v87
	v_cvt_pk_bf16_f32 v106, v80, v81
	v_cvt_pk_bf16_f32 v107, v82, v83
	v_cvt_pk_bf16_f32 v108, v76, v77
	v_cvt_pk_bf16_f32 v109, v78, v79
	v_cvt_pk_bf16_f32 v110, v72, v73
	v_cvt_pk_bf16_f32 v111, v74, v75
	v_cvt_pk_bf16_f32 v112, v68, v69
	v_cvt_pk_bf16_f32 v113, v70, v71
	v_cvt_pk_bf16_f32 v114, v64, v65
	v_cvt_pk_bf16_f32 v115, v66, v67
	v_mov_b32_e32 v169, 0xf149f2ca
	v_mov_b32_e32 v168, 0
	v_mov_b32_e32 v64, 0
	v_mov_b32_e32 v65, 0
	v_mov_b32_e32 v66, 0
	v_mov_b32_e32 v67, 0
	v_mov_b32_e32 v68, 0
	v_mov_b32_e32 v69, 0
	v_mov_b32_e32 v70, 0
	v_mov_b32_e32 v71, 0
	v_mov_b32_e32 v72, 0
	v_mov_b32_e32 v73, 0
	v_mov_b32_e32 v74, 0
	v_mov_b32_e32 v75, 0
	v_mov_b32_e32 v76, 0
	v_mov_b32_e32 v77, 0
	v_mov_b32_e32 v78, 0
	v_mov_b32_e32 v79, 0
	v_mov_b64_e32 v[28:29], v[12:13]
	v_mov_b64_e32 v[26:27], v[10:11]
	v_mov_b64_e32 v[24:25], v[8:9]
	v_mov_b64_e32 v[22:23], v[6:7]
	v_mov_b64_e32 v[20:21], v[4:5]
	v_mov_b64_e32 v[18:19], v[2:3]
	v_mov_b64_e32 v[16:17], v[0:1]
	v_mov_b64_e32 v[44:45], v[12:13]
	v_mov_b64_e32 v[42:43], v[10:11]
	v_mov_b64_e32 v[40:41], v[8:9]
	v_mov_b64_e32 v[38:39], v[6:7]
	v_mov_b64_e32 v[36:37], v[4:5]
	v_mov_b64_e32 v[34:35], v[2:3]
	v_mov_b64_e32 v[32:33], v[0:1]
	v_mov_b64_e32 v[60:61], v[12:13]
	v_mov_b64_e32 v[58:59], v[10:11]
	v_mov_b64_e32 v[56:57], v[8:9]
	v_mov_b64_e32 v[54:55], v[6:7]
	v_mov_b64_e32 v[52:53], v[4:5]
	v_mov_b64_e32 v[50:51], v[2:3]
	v_mov_b64_e32 v[48:49], v[0:1]
	s_add_i32 s60, s16, 1
	s_add_i32 s81, s16, 2
	s_cmp_ge_u32 s81, s50
	s_mov_b32 s59, s61
	s_mov_b32 s83, 0
	s_cbranch_scc1 .LBB0_1016
.LBB0_1015:
	s_mov_b32 s83, 1
; __device__ __forceinline__ void att_qk_sm(const LAS unsigned char* kb, int klane, const bf16x8 (&qf)[12], f32x16 (&o)[4], float& mrun, float& lrun, bf16x8 (&pb)[4]) {
;     constexpr int KP = 400;
;     f32x16 s0, s1;
; #pragma unroll
;     for (int i = 0; i < 16; ++i) { s0[i] = 0.f; s1[i] = 0.f; }
;     bf16x8 ka[3][2];
; #pragma unroll
;     for (int g = 0; g < 2; ++g) { ka[g][0] = *(const LAS bf16x8*)(kb + klane + g * 32); ka[g][1] = *(const LAS bf16x8*)(kb + klane + 32 * KP + g * 32); }
; #pragma unroll
;     for (int g = 0; g < 12; ++g) {
;         if (g < 10) { ka[(g + 2) % 3][0] = *(const LAS bf16x8*)(kb + klane + (g + 2) * 32); ka[(g + 2) % 3][1] = *(const LAS bf16x8*)(kb + klane + 32 * KP + (g + 2) * 32); }
;         __builtin_amdgcn_sched_barrier(0);
;         s0 = __builtin_amdgcn_mfma_f32_32x32x16_bf16(ka[g % 3][0], qf[g], s0, 0, 0, 0);
;         s1 = __builtin_amdgcn_mfma_f32_32x32x16_bf16(ka[g % 3][1], qf[g], s1, 0, 0, 0);
;         __builtin_amdgcn_sched_barrier(0);
;     }
; __device__ __forceinline__ void att_pv(const LAS unsigned char* kb, int vlane, const bf16x8 (&pb)[4], f32x16 (&o)[4]) {
;     constexpr int VP = 320;
;     s16x4 vlo[2][4], vhi[2][4];
;     const unsigned vaddr = (unsigned)(unsigned long)(kb + vlane);
; #pragma unroll
;     for (int d = 0; d < 4; ++d) { TR_READ(vlo[0][d], vaddr, d * 64); TR_READ(vhi[0][d], vaddr, 8 * VP + d * 64); }
; #pragma unroll
;     for (int ks = 0; ks < 4; ++ks) {
;         if (ks < 3) {
; #pragma unroll
;             for (int d = 0; d < 4; ++d) { TR_READ(vlo[(ks + 1) & 1][d], vaddr, ((ks + 1) * 16) * VP + d * 64); TR_READ(vhi[(ks + 1) & 1][d], vaddr, ((ks + 1) * 16 + 8) * VP + d * 64); }
;             TR_WAIT4(8, vlo[ks & 1][0], vlo[ks & 1][1], vlo[ks & 1][2], vlo[ks & 1][3]); TR_WAIT4(8, vhi[ks & 1][0], vhi[ks & 1][1], vhi[ks & 1][2], vhi[ks & 1][3]);
;         } else {
;             TR_WAIT4(0, vlo[ks & 1][0], vlo[ks & 1][1], vlo[ks & 1][2], vlo[ks & 1][3]); TR_WAIT4(0, vhi[ks & 1][0], vhi[ks & 1][1], vhi[ks & 1][2], vhi[ks & 1][3]);
;         }
;         __builtin_amdgcn_sched_barrier(0);
; #pragma unroll
;         for (int d = 0; d < 4; ++d) { const bf16x8 a = __builtin_shufflevector(vlo[ks & 1][d], vhi[ks & 1][d], 0, 1, 2, 3, 4, 5, 6, 7);
;             o[d] = __builtin_amdgcn_mfma_f32_32x32x16_bf16(a, pb[ks], o[d], 0, 0, 0); }
;         __builtin_amdgcn_sched_barrier(0);
;     }
; }
.LBB0_1016:
	s_cmp_lg_u32 s16, 0
	s_cselect_b64 s[4:5], -1, 0
	s_and_b64 s[4:5], s[0:1], s[4:5]
	s_cmp_le_u32 s16, s51
	s_cselect_b64 s[62:63], -1, 0
	s_and_b64 s[4:5], s[4:5], s[62:63]
	s_andn2_b64 vcc, exec, s[4:5]
	s_cbranch_vccnz .LBB0_1018
	s_mul_i32 s4, s17, 0xb400
	v_add_u32_e32 v80, s77, v222
	v_add_u32_e32 v186, 0x6400, v80
	ds_read_b64_tr_b16 v[80:81], v186 offset:0
	ds_read_b64_tr_b16 v[82:83], v186 offset:2560
	ds_read_b64_tr_b16 v[84:85], v186 offset:64
	ds_read_b64_tr_b16 v[86:87], v186 offset:2624
	ds_read_b64_tr_b16 v[88:89], v186 offset:128
	ds_read_b64_tr_b16 v[90:91], v186 offset:2688
	ds_read_b64_tr_b16 v[92:93], v186 offset:192
	ds_read_b64_tr_b16 v[94:95], v186 offset:2752
	ds_read_b64_tr_b16 v[170:171], v186 offset:5120
	ds_read_b64_tr_b16 v[172:173], v186 offset:7680
	ds_read_b64_tr_b16 v[174:175], v186 offset:5184
	ds_read_b64_tr_b16 v[176:177], v186 offset:7744
	ds_read_b64_tr_b16 v[178:179], v186 offset:5248
	ds_read_b64_tr_b16 v[180:181], v186 offset:7808
	ds_read_b64_tr_b16 v[182:183], v186 offset:5312
	ds_read_b64_tr_b16 v[184:185], v186 offset:7872
	s_nop 0
	s_waitcnt lgkmcnt(8)
	s_waitcnt lgkmcnt(8)
	s_nop 0
	v_mfma_f32_32x32x16_bf16 v[48:63], v[80:83], v[76:79], v[48:63]
	v_mfma_f32_32x32x16_bf16 v[32:47], v[84:87], v[76:79], v[32:47]
	v_mfma_f32_32x32x16_bf16 v[16:31], v[88:91], v[76:79], v[16:31]
	v_mfma_f32_32x32x16_bf16 v[0:15], v[92:95], v[76:79], v[0:15]
	ds_read_b64_tr_b16 v[80:81], v186 offset:10240
	ds_read_b64_tr_b16 v[82:83], v186 offset:12800
	ds_read_b64_tr_b16 v[84:85], v186 offset:10304
	ds_read_b64_tr_b16 v[86:87], v186 offset:12864
	ds_read_b64_tr_b16 v[88:89], v186 offset:10368
	ds_read_b64_tr_b16 v[90:91], v186 offset:12928
	ds_read_b64_tr_b16 v[92:93], v186 offset:10432
	ds_read_b64_tr_b16 v[94:95], v186 offset:12992
	s_waitcnt lgkmcnt(8)
	s_waitcnt lgkmcnt(8)
	s_nop 0
	v_mfma_f32_32x32x16_bf16 v[48:63], v[170:173], v[72:75], v[48:63]
	v_mfma_f32_32x32x16_bf16 v[32:47], v[174:177], v[72:75], v[32:47]
	v_mfma_f32_32x32x16_bf16 v[16:31], v[178:181], v[72:75], v[16:31]
	v_mfma_f32_32x32x16_bf16 v[0:15], v[182:185], v[72:75], v[0:15]
	ds_read_b64_tr_b16 v[170:171], v186 offset:15360
	ds_read_b64_tr_b16 v[172:173], v186 offset:17920
	ds_read_b64_tr_b16 v[174:175], v186 offset:15424
	ds_read_b64_tr_b16 v[176:177], v186 offset:17984
	ds_read_b64_tr_b16 v[178:179], v186 offset:15488
	ds_read_b64_tr_b16 v[180:181], v186 offset:18048
	ds_read_b64_tr_b16 v[182:183], v186 offset:15552
	ds_read_b64_tr_b16 v[184:185], v186 offset:18112
	s_waitcnt lgkmcnt(8)
	s_waitcnt lgkmcnt(8)
	s_nop 0
	v_mfma_f32_32x32x16_bf16 v[48:63], v[80:83], v[68:71], v[48:63]
	v_mfma_f32_32x32x16_bf16 v[32:47], v[84:87], v[68:71], v[32:47]
	v_mfma_f32_32x32x16_bf16 v[16:31], v[88:91], v[68:71], v[16:31]
	v_mfma_f32_32x32x16_bf16 v[0:15], v[92:95], v[68:71], v[0:15]
	s_waitcnt lgkmcnt(0)
	s_waitcnt lgkmcnt(0)
	s_nop 0
	v_mfma_f32_32x32x16_bf16 v[48:63], v[170:173], v[64:67], v[48:63]
	v_mfma_f32_32x32x16_bf16 v[32:47], v[174:177], v[64:67], v[32:47]
	v_mfma_f32_32x32x16_bf16 v[16:31], v[178:181], v[64:67], v[16:31]
	v_mfma_f32_32x32x16_bf16 v[0:15], v[182:185], v[64:67], v[0:15]
.LBB0_1018:
	s_cmp_gt_u32 s16, s6
	s_cselect_b64 s[16:17], -1, 0
	s_and_b64 vcc, exec, s[16:17]
	s_mul_i32 s61, s58, 0xb400
	s_cbranch_vccnz .Latt_skipq
	v_add_u32_e32 v194, s74, v223
	ds_read_b128 v[64:67], v194
	ds_read_b128 v[170:173], v194 offset:32
	ds_read_b128 v[174:177], v194 offset:12832
	ds_read_b128 v[178:181], v194 offset:12864
	ds_read_b128 v[182:185], v194 offset:64
	ds_read_b128 v[68:71], v194 offset:12800
	s_waitcnt lgkmcnt(0)
	v_mfma_f32_32x32x16_bf16 v[80:95], v[64:67], v[96:99], 0
	v_mfma_f32_32x32x16_bf16 v[64:79], v[68:71], v[96:99], 0
	ds_read_b128 v[186:189], v194 offset:96
	ds_read_b128 v[190:193], v194 offset:12896
	v_mfma_f32_32x32x16_bf16 v[80:95], v[170:173], v[100:103], v[80:95]
	v_mfma_f32_32x32x16_bf16 v[64:79], v[174:177], v[100:103], v[64:79]
	ds_read_b128 v[170:173], v194 offset:128
	ds_read_b128 v[174:177], v194 offset:12928
	v_mfma_f32_32x32x16_bf16 v[80:95], v[182:185], v[104:107], v[80:95]
	v_mfma_f32_32x32x16_bf16 v[64:79], v[178:181], v[104:107], v[64:79]
	ds_read_b128 v[178:181], v194 offset:160
	ds_read_b128 v[182:185], v194 offset:12960
	s_waitcnt lgkmcnt(0)
	v_mfma_f32_32x32x16_bf16 v[80:95], v[186:189], v[108:111], v[80:95]
	v_mfma_f32_32x32x16_bf16 v[64:79], v[190:193], v[108:111], v[64:79]
	ds_read_b128 v[186:189], v194 offset:192
	ds_read_b128 v[190:193], v194 offset:12992
	v_mfma_f32_32x32x16_bf16 v[80:95], v[170:173], v[112:115], v[80:95]
	v_mfma_f32_32x32x16_bf16 v[64:79], v[174:177], v[112:115], v[64:79]
	ds_read_b128 v[170:173], v194 offset:224
	ds_read_b128 v[174:177], v194 offset:13024
	v_mfma_f32_32x32x16_bf16 v[80:95], v[178:181], v[116:119], v[80:95]
	v_mfma_f32_32x32x16_bf16 v[64:79], v[182:185], v[116:119], v[64:79]
	ds_read_b128 v[178:181], v194 offset:256
	ds_read_b128 v[182:185], v194 offset:13056
	s_waitcnt lgkmcnt(0)
	v_mfma_f32_32x32x16_bf16 v[80:95], v[186:189], v[120:123], v[80:95]
	v_mfma_f32_32x32x16_bf16 v[64:79], v[190:193], v[120:123], v[64:79]
	ds_read_b128 v[186:189], v194 offset:288
	ds_read_b128 v[190:193], v194 offset:13088
	v_mfma_f32_32x32x16_bf16 v[80:95], v[170:173], v[124:127], v[80:95]
	v_mfma_f32_32x32x16_bf16 v[64:79], v[174:177], v[124:127], v[64:79]
	ds_read_b128 v[170:173], v194 offset:320
	ds_read_b128 v[174:177], v194 offset:13120
	v_mfma_f32_32x32x16_bf16 v[80:95], v[178:181], v[128:131], v[80:95]
	v_mfma_f32_32x32x16_bf16 v[64:79], v[182:185], v[128:131], v[64:79]
	ds_read_b128 v[178:181], v194 offset:352
	ds_read_b128 v[182:185], v194 offset:13152
	s_waitcnt lgkmcnt(0)
	v_mfma_f32_32x32x16_bf16 v[80:95], v[186:189], v[132:135], v[80:95]
	v_mfma_f32_32x32x16_bf16 v[64:79], v[190:193], v[132:135], v[64:79]
	v_mfma_f32_32x32x16_bf16 v[80:95], v[170:173], v[136:139], v[80:95]
	v_mfma_f32_32x32x16_bf16 v[64:79], v[174:177], v[136:139], v[64:79]
	v_mfma_f32_32x32x16_bf16 v[80:95], v[178:181], v[140:143], v[80:95]
	v_mfma_f32_32x32x16_bf16 v[64:79], v[182:185], v[140:143], v[64:79]
	s_cmp_lg_u32 s83, 0
	s_cbranch_scc0 .Latt_noissue_q
	s_mov_b64 s[4:5], s[10:11]
	s_cmp_eq_u32 s33, 0
	s_cselect_b32 s82, s76, s80
	s_add_i32 m0, s76, s19
	v_lshl_add_u64 v[172:173], s[4:5], 0, v[144:145]
	global_load_lds_dwordx4 v[172:173], off
	s_add_i32 m0, s76, s20
	v_lshl_add_u64 v[172:173], s[4:5], 0, v[146:147]
	global_load_lds_dwordx4 v[172:173], off
	s_add_i32 m0, s76, s21
	v_lshl_add_u64 v[172:173], s[4:5], 0, v[148:149]
	global_load_lds_dwordx4 v[172:173], off
	s_add_i32 m0, s82, s22
	v_lshl_add_u64 v[172:173], s[4:5], 0, v[150:151]
	global_load_lds_dwordx4 v[172:173], off
	s_add_i32 m0, s80, s23
	v_lshl_add_u64 v[172:173], s[4:5], 0, v[156:157]
	global_load_lds_dwordx4 v[172:173], off
	s_add_i32 m0, s80, s24
	v_lshl_add_u64 v[172:173], s[4:5], 0, v[154:155]
	global_load_lds_dwordx4 v[172:173], off
	s_branch .Latt_issued_q
; __device__ __forceinline__ void att_qk_sm(const LAS unsigned char* kb, int klane, const bf16x8 (&qf)[12], f32x16 (&o)[4], float& mrun, float& lrun, bf16x8 (&pb)[4]) {
;     ...
;     float mx = fmaxf(s0[0], s1[0]);
; #pragma unroll
;     for (int i = 1; i < 16; ++i) asm("v_max3_f32 %0, %1, %2, %3" : "=v"(mx) : "v"(mx), "v"(s0[i]), "v"(s1[i]));
;     { const auto rr = __builtin_amdgcn_permlane32_swap(__float_as_uint(mx), __float_as_uint(mx), false, false);
;       mx = fmaxf(__uint_as_float(rr[0]), __uint_as_float(rr[1])); }
;     if (!__all(mx - mrun <= 8.0f)) {
;         const float mn = fmaxf(mrun, mx), al = __builtin_amdgcn_exp2f(mrun - mn);
;         mrun = mn; lrun *= al;
; #pragma unroll
;         for (int d = 0; d < 4; ++d) o[d] = o[d] * al;
;     }
.Latt_noissue_q:
	s_nop 11
.Latt_issued_q:
	v_max_f32_e32 v170, v64, v64
	v_max_f32_e32 v171, v80, v80
	v_max_f32_e32 v170, v171, v170
	v_max3_f32 v170, v170, v81, v65
	s_nop 0
	v_max3_f32 v170, v170, v82, v66
	s_nop 0
	v_max3_f32 v170, v170, v83, v67
	s_nop 0
	v_max3_f32 v170, v170, v84, v68
	s_nop 0
	v_max3_f32 v170, v170, v85, v69
	s_nop 0
	v_max3_f32 v170, v170, v86, v70
	s_nop 0
	v_max3_f32 v170, v170, v87, v71
	s_nop 0
	v_max3_f32 v170, v170, v88, v72
	s_nop 0
	v_max3_f32 v170, v170, v89, v73
	s_nop 0
	v_max3_f32 v170, v170, v90, v74
	s_nop 0
	v_max3_f32 v170, v170, v91, v75
	s_nop 0
	v_max3_f32 v170, v170, v92, v76
	s_nop 0
	v_max3_f32 v170, v170, v93, v77
	s_nop 0
	v_max3_f32 v170, v170, v94, v78
	s_nop 0
	v_max3_f32 v170, v170, v95, v79
	s_nop 0
	v_mov_b32_e32 v171, v170
	s_nop 1
	v_permlane32_swap_b32_e32 v170, v171
	v_max_f32_e32 v171, v171, v171
	v_max_f32_e32 v170, v170, v170
	v_max_f32_e32 v170, v170, v171
	v_sub_f32_e32 v171, v170, v169
	v_cmp_ge_f32_e32 vcc, s37, v171
	s_cmp_eq_u64 vcc, exec
	s_cbranch_scc1 .LBB0_1021
	v_max_f32_e32 v170, v170, v170
	v_max_f32_e32 v171, v169, v169
	v_max_f32_e32 v171, v171, v170
	v_sub_f32_e32 v169, v169, v171
	v_exp_f32_e32 v170, v169
	v_mov_b32_e32 v169, v171
	v_mul_f32_e32 v168, v168, v170
	v_pk_mul_f32 v[62:63], v[62:63], v[170:171] op_sel_hi:[1,0]
	v_pk_mul_f32 v[60:61], v[60:61], v[170:171] op_sel_hi:[1,0]
	v_pk_mul_f32 v[58:59], v[58:59], v[170:171] op_sel_hi:[1,0]
	v_pk_mul_f32 v[56:57], v[56:57], v[170:171] op_sel_hi:[1,0]
	v_pk_mul_f32 v[54:55], v[54:55], v[170:171] op_sel_hi:[1,0]
	v_pk_mul_f32 v[52:53], v[52:53], v[170:171] op_sel_hi:[1,0]
	v_pk_mul_f32 v[50:51], v[50:51], v[170:171] op_sel_hi:[1,0]
	v_pk_mul_f32 v[48:49], v[48:49], v[170:171] op_sel_hi:[1,0]
	v_pk_mul_f32 v[46:47], v[46:47], v[170:171] op_sel_hi:[1,0]
	v_pk_mul_f32 v[44:45], v[44:45], v[170:171] op_sel_hi:[1,0]
	v_pk_mul_f32 v[42:43], v[42:43], v[170:171] op_sel_hi:[1,0]
	v_pk_mul_f32 v[40:41], v[40:41], v[170:171] op_sel_hi:[1,0]
	v_pk_mul_f32 v[38:39], v[38:39], v[170:171] op_sel_hi:[1,0]
	v_pk_mul_f32 v[36:37], v[36:37], v[170:171] op_sel_hi:[1,0]
	v_pk_mul_f32 v[34:35], v[34:35], v[170:171] op_sel_hi:[1,0]
	v_pk_mul_f32 v[32:33], v[32:33], v[170:171] op_sel_hi:[1,0]
	v_pk_mul_f32 v[30:31], v[30:31], v[170:171] op_sel_hi:[1,0]
	v_pk_mul_f32 v[28:29], v[28:29], v[170:171] op_sel_hi:[1,0]
	v_pk_mul_f32 v[26:27], v[26:27], v[170:171] op_sel_hi:[1,0]
	v_pk_mul_f32 v[24:25], v[24:25], v[170:171] op_sel_hi:[1,0]
	v_pk_mul_f32 v[22:23], v[22:23], v[170:171] op_sel_hi:[1,0]
	v_pk_mul_f32 v[20:21], v[20:21], v[170:171] op_sel_hi:[1,0]
	v_pk_mul_f32 v[18:19], v[18:19], v[170:171] op_sel_hi:[1,0]
	v_pk_mul_f32 v[16:17], v[16:17], v[170:171] op_sel_hi:[1,0]
	v_pk_mul_f32 v[14:15], v[14:15], v[170:171] op_sel_hi:[1,0]
	v_pk_mul_f32 v[12:13], v[12:13], v[170:171] op_sel_hi:[1,0]
	v_pk_mul_f32 v[10:11], v[10:11], v[170:171] op_sel_hi:[1,0]
	v_pk_mul_f32 v[8:9], v[8:9], v[170:171] op_sel_hi:[1,0]
	v_pk_mul_f32 v[6:7], v[6:7], v[170:171] op_sel_hi:[1,0]
	v_pk_mul_f32 v[4:5], v[4:5], v[170:171] op_sel_hi:[1,0]
	v_pk_mul_f32 v[2:3], v[2:3], v[170:171] op_sel_hi:[1,0]
	v_pk_mul_f32 v[0:1], v[0:1], v[170:171] op_sel_hi:[1,0]

; #define LAS __attribute__((address_space(3)))
; #define TR_READ(dst, addr, off) asm volatile("ds_read_b64_tr_b16 %0, %1 offset:%c2" : "=v"(dst) : "v"(addr), "i"(off) : "memory")
; #define TR_WAIT4(n, a, b, c, d) asm volatile("s_waitcnt lgkmcnt(" #n ")" : "+v"(a), "+v"(b), "+v"(c), "+v"(d) :: "memory")
; __device__ __forceinline__ void att_pv(const LAS unsigned char* kb, int vlane, const bf16x8 (&pb)[4], f32x16 (&o)[4]) {
;     constexpr int VP = 320;
;     s16x4 vlo[2][4], vhi[2][4];
;     const unsigned vaddr = (unsigned)(unsigned long)(kb + vlane);
; #pragma unroll
;     for (int d = 0; d < 4; ++d) { TR_READ(vlo[0][d], vaddr, d * 64); TR_READ(vhi[0][d], vaddr, 8 * VP + d * 64); }
; #pragma unroll
;     for (int ks = 0; ks < 4; ++ks) {
;         if (ks < 3) {
; #pragma unroll
;             for (int d = 0; d < 4; ++d) { TR_READ(vlo[(ks + 1) & 1][d], vaddr, ((ks + 1) * 16) * VP + d * 64); TR_READ(vhi[(ks + 1) & 1][d], vaddr, ((ks + 1) * 16 + 8) * VP + d * 64); }
;             TR_WAIT4(8, vlo[ks & 1][0], vlo[ks & 1][1], vlo[ks & 1][2], vlo[ks & 1][3]); TR_WAIT4(8, vhi[ks & 1][0], vhi[ks & 1][1], vhi[ks & 1][2], vhi[ks & 1][3]);
;         } else {
;             TR_WAIT4(0, vlo[ks & 1][0], vlo[ks & 1][1], vlo[ks & 1][2], vlo[ks & 1][3]); TR_WAIT4(0, vhi[ks & 1][0], vhi[ks & 1][1], vhi[ks & 1][2], vhi[ks & 1][3]);
;         }
;         __builtin_amdgcn_sched_barrier(0);
; #pragma unroll
;         for (int d = 0; d < 4; ++d) { const bf16x8 a = __builtin_shufflevector(vlo[ks & 1][d], vhi[ks & 1][d], 0, 1, 2, 3, 4, 5, 6, 7);
;             o[d] = __builtin_amdgcn_mfma_f32_32x32x16_bf16(a, pb[ks], o[d], 0, 0, 0); }
;         __builtin_amdgcn_sched_barrier(0);
;     }
; }
; __device__ __forceinline__ void att_mfma(const Params& P, LAS unsigned char* lds, int wave) {
;     ...
;         for (int kt = 0; kt < ntile; ++kt) {
;             if (kt + 1 < ntile) ATT_ISSUE(kvb + (size_t)(kt + 1) * 327680, lds + bnext * BUF);
;             if (!roleA && kt >= 1 && kt - 1 <= my_last) att_pv(lds + bprev * BUF, vlane, pb, o);
;             if (kt <= my_last) att_qk_sm(lds + bcur * BUF, klane, qf, o, mrun, lrun, pb);
;             if (roleA && kt <= my_last) att_pv(lds + bcur * BUF, vlane, pb, o);
;             ATT_BAR();
;             bprev = bcur; bcur = bnext; bnext = bnext == 2 ? 0 : bnext + 1;
;         }
.LBB0_1022:
	s_or_b64 s[4:5], s[0:1], s[16:17]
	s_and_b64 vcc, exec, s[4:5]
	s_cbranch_vccnz .LBB0_1024
	v_add_u32_e32 v80, s78, v222
	v_add_u32_e32 v186, 0x6400, v80
	ds_read_b64_tr_b16 v[80:81], v186 offset:0
	ds_read_b64_tr_b16 v[82:83], v186 offset:2560
	ds_read_b64_tr_b16 v[84:85], v186 offset:64
	ds_read_b64_tr_b16 v[86:87], v186 offset:2624
	ds_read_b64_tr_b16 v[88:89], v186 offset:128
	ds_read_b64_tr_b16 v[90:91], v186 offset:2688
	ds_read_b64_tr_b16 v[92:93], v186 offset:192
	ds_read_b64_tr_b16 v[94:95], v186 offset:2752
	ds_read_b64_tr_b16 v[170:171], v186 offset:5120
	ds_read_b64_tr_b16 v[172:173], v186 offset:7680
	ds_read_b64_tr_b16 v[174:175], v186 offset:5184
	ds_read_b64_tr_b16 v[176:177], v186 offset:7744
	ds_read_b64_tr_b16 v[178:179], v186 offset:5248
	ds_read_b64_tr_b16 v[180:181], v186 offset:7808
	ds_read_b64_tr_b16 v[182:183], v186 offset:5312
	ds_read_b64_tr_b16 v[184:185], v186 offset:7872
	s_nop 0
	s_waitcnt lgkmcnt(8)
	s_waitcnt lgkmcnt(8)
	s_nop 0
	v_mfma_f32_32x32x16_bf16 v[48:63], v[80:83], v[76:79], v[48:63]
	v_mfma_f32_32x32x16_bf16 v[32:47], v[84:87], v[76:79], v[32:47]
	v_mfma_f32_32x32x16_bf16 v[16:31], v[88:91], v[76:79], v[16:31]
	v_mfma_f32_32x32x16_bf16 v[0:15], v[92:95], v[76:79], v[0:15]
	ds_read_b64_tr_b16 v[80:81], v186 offset:10240
	ds_read_b64_tr_b16 v[82:83], v186 offset:12800
	ds_read_b64_tr_b16 v[84:85], v186 offset:10304
	ds_read_b64_tr_b16 v[86:87], v186 offset:12864
	ds_read_b64_tr_b16 v[88:89], v186 offset:10368
	ds_read_b64_tr_b16 v[90:91], v186 offset:12928
	ds_read_b64_tr_b16 v[92:93], v186 offset:10432
	ds_read_b64_tr_b16 v[94:95], v186 offset:12992
	s_waitcnt lgkmcnt(8)
	s_waitcnt lgkmcnt(8)
	s_nop 0
	v_mfma_f32_32x32x16_bf16 v[48:63], v[170:173], v[72:75], v[48:63]
	v_mfma_f32_32x32x16_bf16 v[32:47], v[174:177], v[72:75], v[32:47]
	v_mfma_f32_32x32x16_bf16 v[16:31], v[178:181], v[72:75], v[16:31]
	v_mfma_f32_32x32x16_bf16 v[0:15], v[182:185], v[72:75], v[0:15]
	ds_read_b64_tr_b16 v[170:171], v186 offset:15360
	ds_read_b64_tr_b16 v[172:173], v186 offset:17920
	ds_read_b64_tr_b16 v[174:175], v186 offset:15424
	ds_read_b64_tr_b16 v[176:177], v186 offset:17984
	ds_read_b64_tr_b16 v[178:179], v186 offset:15488
	ds_read_b64_tr_b16 v[180:181], v186 offset:18048
	ds_read_b64_tr_b16 v[182:183], v186 offset:15552
	ds_read_b64_tr_b16 v[184:185], v186 offset:18112
	s_waitcnt lgkmcnt(8)
	s_waitcnt lgkmcnt(8)
	s_nop 0
	v_mfma_f32_32x32x16_bf16 v[48:63], v[80:83], v[68:71], v[48:63]
	v_mfma_f32_32x32x16_bf16 v[32:47], v[84:87], v[68:71], v[32:47]
	v_mfma_f32_32x32x16_bf16 v[16:31], v[88:91], v[68:71], v[16:31]
	v_mfma_f32_32x32x16_bf16 v[0:15], v[92:95], v[68:71], v[0:15]
	s_waitcnt lgkmcnt(0)
	s_waitcnt lgkmcnt(0)
	s_nop 0
	v_mfma_f32_32x32x16_bf16 v[48:63], v[170:173], v[64:67], v[48:63]
	v_mfma_f32_32x32x16_bf16 v[32:47], v[174:177], v[64:67], v[32:47]
	v_mfma_f32_32x32x16_bf16 v[16:31], v[178:181], v[64:67], v[16:31]
	v_mfma_f32_32x32x16_bf16 v[0:15], v[182:185], v[64:67], v[0:15]
.LBB0_1024:
	s_add_i32 s81, s60, 1
	s_cmp_lt_u32 s81, s50
	s_cbranch_scc1 .Latt_wait6
	s_waitcnt vmcnt(0)
	s_branch .Latt_waitd
.Latt_wait6:
	s_waitcnt vmcnt(6)
.Latt_waitd:
	s_add_i32 s4, s59, 1
	s_cmp_lg_u32 s59, 2
	s_waitcnt lgkmcnt(0)
	s_barrier
	s_cselect_b32 s61, s4, 0
	s_add_u32 s10, s10, 0x50000
	s_addc_u32 s11, s11, 0
	s_cmp_eq_u32 s50, s60
	s_cbranch_scc1 .LBB0_1026
	s_mov_b32 s16, s60
	s_mov_b32 s17, s58
	s_mov_b32 s58, s59
	s_add_i32 s60, s16, 1
	s_mov_b32 s81, s74
	s_mov_b32 s74, s75
	s_mov_b32 s75, s76
	s_mov_b32 s76, s81
	s_mov_b32 s81, s77
	s_mov_b32 s77, s78
	s_mov_b32 s78, s79
	s_mov_b32 s79, s80
	s_mov_b32 s80, s81
	s_add_i32 s81, s16, 2
	s_cmp_ge_u32 s81, s50
	s_mov_b32 s59, s61
	s_mov_b32 s83, 0
	s_cbranch_scc0 .LBB0_1015
	s_branch .LBB0_1016
; #define LAS __attribute__((address_space(3)))
; #define TR_READ(dst, addr, off) asm volatile("ds_read_b64_tr_b16 %0, %1 offset:%c2" : "=v"(dst) : "v"(addr), "i"(off) : "memory")
; #define TR_WAIT4(n, a, b, c, d) asm volatile("s_waitcnt lgkmcnt(" #n ")" : "+v"(a), "+v"(b), "+v"(c), "+v"(d) :: "memory")
; __device__ __forceinline__ void att_pv(const LAS unsigned char* kb, int vlane, const bf16x8 (&pb)[4], f32x16 (&o)[4]) {
;     constexpr int VP = 320;
;     s16x4 vlo[2][4], vhi[2][4];
;     const unsigned vaddr = (unsigned)(unsigned long)(kb + vlane);
; #pragma unroll
;     for (int d = 0; d < 4; ++d) { TR_READ(vlo[0][d], vaddr, d * 64); TR_READ(vhi[0][d], vaddr, 8 * VP + d * 64); }
; #pragma unroll
;     for (int ks = 0; ks < 4; ++ks) {
;         if (ks < 3) {
; #pragma unroll
;             for (int d = 0; d < 4; ++d) { TR_READ(vlo[(ks + 1) & 1][d], vaddr, ((ks + 1) * 16) * VP + d * 64); TR_READ(vhi[(ks + 1) & 1][d], vaddr, ((ks + 1) * 16 + 8) * VP + d * 64); }
;             TR_WAIT4(8, vlo[ks & 1][0], vlo[ks & 1][1], vlo[ks & 1][2], vlo[ks & 1][3]); TR_WAIT4(8, vhi[ks & 1][0], vhi[ks & 1][1], vhi[ks & 1][2], vhi[ks & 1][3]);
;         } else {
;             TR_WAIT4(0, vlo[ks & 1][0], vlo[ks & 1][1], vlo[ks & 1][2], vlo[ks & 1][3]); TR_WAIT4(0, vhi[ks & 1][0], vhi[ks & 1][1], vhi[ks & 1][2], vhi[ks & 1][3]);
;         }
;         __builtin_amdgcn_sched_barrier(0);
; #pragma unroll
;         for (int d = 0; d < 4; ++d) { const bf16x8 a = __builtin_shufflevector(vlo[ks & 1][d], vhi[ks & 1][d], 0, 1, 2, 3, 4, 5, 6, 7);
;             o[d] = __builtin_amdgcn_mfma_f32_32x32x16_bf16(a, pb[ks], o[d], 0, 0, 0); }
;         __builtin_amdgcn_sched_barrier(0);
;     }
; }
; __device__ __forceinline__ void att_mfma(const Params& P, LAS unsigned char* lds, int wave) {
;     ...
;             if (kt + 1 < ntile) ATT_ISSUE(kvb + (size_t)(kt + 1) * 327680, lds + bnext * BUF);
;             if (!roleA && kt >= 1 && kt - 1 <= my_last) att_pv(lds + bprev * BUF, vlane, pb, o);
;             if (kt <= my_last) att_qk_sm(lds + bcur * BUF, klane, qf, o, mrun, lrun, pb);
;             if (roleA && kt <= my_last) att_pv(lds + bcur * BUF, vlane, pb, o);
;             ATT_BAR();
;             bprev = bcur; bcur = bnext; bnext = bnext == 2 ? 0 : bnext + 1;
;         }
;         if (!roleA && ntile - 1 <= my_last) att_pv(lds + bprev * BUF, vlane, pb, o);
.Latt_skipq:
	s_cmp_lg_u32 s83, 0
	s_cbranch_scc0 .LBB0_1022
	s_mov_b64 s[4:5], s[10:11]
	s_cmp_eq_u32 s33, 0
	s_cselect_b32 s82, s76, s80
	s_add_i32 m0, s76, s19
	v_lshl_add_u64 v[172:173], s[4:5], 0, v[144:145]
	global_load_lds_dwordx4 v[172:173], off
	s_add_i32 m0, s76, s20
	v_lshl_add_u64 v[172:173], s[4:5], 0, v[146:147]
	global_load_lds_dwordx4 v[172:173], off
	s_add_i32 m0, s76, s21
	v_lshl_add_u64 v[172:173], s[4:5], 0, v[148:149]
	global_load_lds_dwordx4 v[172:173], off
	s_add_i32 m0, s82, s22
	v_lshl_add_u64 v[172:173], s[4:5], 0, v[150:151]
	global_load_lds_dwordx4 v[172:173], off
	s_add_i32 m0, s80, s23
	v_lshl_add_u64 v[172:173], s[4:5], 0, v[156:157]
	global_load_lds_dwordx4 v[172:173], off
	s_add_i32 m0, s80, s24
	v_lshl_add_u64 v[172:173], s[4:5], 0, v[154:155]
	global_load_lds_dwordx4 v[172:173], off
	s_branch .LBB0_1022
.LBB0_1026:
	s_and_b64 vcc, exec, s[8:9]
	s_cbranch_vccz .LBB0_1007
	s_mul_i32 s4, s58, 0xb400
	v_add_u32_e32 v80, s78, v222
	v_add_u32_e32 v112, 0x6400, v80
	ds_read_b64_tr_b16 v[80:81], v112 offset:0
	ds_read_b64_tr_b16 v[82:83], v112 offset:2560
	ds_read_b64_tr_b16 v[84:85], v112 offset:64
	ds_read_b64_tr_b16 v[86:87], v112 offset:2624
	ds_read_b64_tr_b16 v[88:89], v112 offset:128
	ds_read_b64_tr_b16 v[90:91], v112 offset:2688
	ds_read_b64_tr_b16 v[92:93], v112 offset:192
	ds_read_b64_tr_b16 v[94:95], v112 offset:2752
	ds_read_b64_tr_b16 v[96:97], v112 offset:5120
	ds_read_b64_tr_b16 v[98:99], v112 offset:7680
	ds_read_b64_tr_b16 v[100:101], v112 offset:5184
	ds_read_b64_tr_b16 v[102:103], v112 offset:7744
	ds_read_b64_tr_b16 v[104:105], v112 offset:5248
	ds_read_b64_tr_b16 v[106:107], v112 offset:7808
	ds_read_b64_tr_b16 v[108:109], v112 offset:5312
	ds_read_b64_tr_b16 v[110:111], v112 offset:7872
	s_nop 0
	s_waitcnt lgkmcnt(8)
	s_waitcnt lgkmcnt(8)
	s_nop 0
	v_mfma_f32_32x32x16_bf16 v[48:63], v[80:83], v[76:79], v[48:63]
	v_mfma_f32_32x32x16_bf16 v[32:47], v[84:87], v[76:79], v[32:47]
	v_mfma_f32_32x32x16_bf16 v[16:31], v[88:91], v[76:79], v[16:31]
	v_mfma_f32_32x32x16_bf16 v[0:15], v[92:95], v[76:79], v[0:15]
	ds_read_b64_tr_b16 v[76:77], v112 offset:10240
	ds_read_b64_tr_b16 v[78:79], v112 offset:12800
	ds_read_b64_tr_b16 v[80:81], v112 offset:10304
	ds_read_b64_tr_b16 v[82:83], v112 offset:12864
	ds_read_b64_tr_b16 v[84:85], v112 offset:10368
	ds_read_b64_tr_b16 v[86:87], v112 offset:12928
	ds_read_b64_tr_b16 v[88:89], v112 offset:10432
	ds_read_b64_tr_b16 v[90:91], v112 offset:12992
	s_waitcnt lgkmcnt(8)
	s_waitcnt lgkmcnt(8)
	s_nop 0
	v_mfma_f32_32x32x16_bf16 v[48:63], v[96:99], v[72:75], v[48:63]
	v_mfma_f32_32x32x16_bf16 v[32:47], v[100:103], v[72:75], v[32:47]
	v_mfma_f32_32x32x16_bf16 v[16:31], v[104:107], v[72:75], v[16:31]
	v_mfma_f32_32x32x16_bf16 v[0:15], v[108:111], v[72:75], v[0:15]
	ds_read_b64_tr_b16 v[72:73], v112 offset:15360
	ds_read_b64_tr_b16 v[74:75], v112 offset:17920
	ds_read_b64_tr_b16 v[92:93], v112 offset:15424
	ds_read_b64_tr_b16 v[94:95], v112 offset:17984
	ds_read_b64_tr_b16 v[96:97], v112 offset:15488
	ds_read_b64_tr_b16 v[98:99], v112 offset:18048
	ds_read_b64_tr_b16 v[100:101], v112 offset:15552
	ds_read_b64_tr_b16 v[102:103], v112 offset:18112
	s_waitcnt lgkmcnt(8)
	s_waitcnt lgkmcnt(8)
	s_nop 0
	v_mfma_f32_32x32x16_bf16 v[48:63], v[76:79], v[68:71], v[48:63]
	v_mfma_f32_32x32x16_bf16 v[32:47], v[80:83], v[68:71], v[32:47]
	v_mfma_f32_32x32x16_bf16 v[16:31], v[84:87], v[68:71], v[16:31]
	v_mfma_f32_32x32x16_bf16 v[0:15], v[88:91], v[68:71], v[0:15]
	s_waitcnt lgkmcnt(0)
	s_waitcnt lgkmcnt(0)
	s_nop 0
	v_mfma_f32_32x32x16_bf16 v[48:63], v[72:75], v[64:67], v[48:63]
	v_mfma_f32_32x32x16_bf16 v[32:47], v[92:95], v[64:67], v[32:47]
	v_mfma_f32_32x32x16_bf16 v[16:31], v[96:99], v[64:67], v[16:31]
	v_mfma_f32_32x32x16_bf16 v[0:15], v[100:103], v[64:67], v[0:15]
	s_branch .LBB0_1007
